# P0 prologue p->bf16 stream: rolling pipeline with 16 loads in flight per lane (fast path when wave stride = 2048x64), v_cvt_pk_bf16_f32 RNE
# baseline (speedup 1.0000x reference)
.LBB0_22:
	v_readlane_b32 s2, v251, 40
	s_cmp_lg_u32 s2, s8
	s_mov_b64 s[8:9], -1
	s_cbranch_scc0 .LBB0_39
	s_andn2_b64 vcc, exec, s[0:1]
	s_cbranch_vccnz .LBB0_33
	s_mov_b64 s[8:9], 0
	v_mov_b64_e32 v[56:57], v[18:19]
	v_mov_b64_e32 v[58:59], v[16:17]
	v_mov_b64_e32 v[60:61], v[0:1]
	s_cmp_eq_u64 s[90:91], 0x20000
	s_cbranch_scc0 .LBB0_28
	v_readfirstlane_b32 s98, v18
	v_readfirstlane_b32 s99, v19
	v_readfirstlane_b32 s100, v16
	v_readfirstlane_b32 s101, v17
	s_nop 4
	v_subrev_u32_e32 v244, s98, v18
	v_subrev_u32_e32 v245, s100, v16
	global_load_dwordx4 v[154:157], v244, s[98:99]
	global_load_dwordx4 v[158:161], v244, s[98:99] offset:16
	s_add_u32 s98, s98, 0x400000
	s_addc_u32 s99, s99, 0
	global_load_dwordx4 v[162:165], v244, s[98:99]
	global_load_dwordx4 v[166:169], v244, s[98:99] offset:16
	s_add_u32 s98, s98, 0x400000
	s_addc_u32 s99, s99, 0
	global_load_dwordx4 v[170:173], v244, s[98:99]
	global_load_dwordx4 v[174:177], v244, s[98:99] offset:16
	s_add_u32 s98, s98, 0x400000
	s_addc_u32 s99, s99, 0
	global_load_dwordx4 v[178:181], v244, s[98:99]
	global_load_dwordx4 v[182:185], v244, s[98:99] offset:16
	s_add_u32 s98, s98, 0x400000
	s_addc_u32 s99, s99, 0
	global_load_dwordx4 v[186:189], v244, s[98:99]
	global_load_dwordx4 v[190:193], v244, s[98:99] offset:16
	s_add_u32 s98, s98, 0x400000
	s_addc_u32 s99, s99, 0
	global_load_dwordx4 v[194:197], v244, s[98:99]
	global_load_dwordx4 v[198:201], v244, s[98:99] offset:16
	s_add_u32 s98, s98, 0x400000
	s_addc_u32 s99, s99, 0
	global_load_dwordx4 v[208:211], v244, s[98:99]
	global_load_dwordx4 v[212:215], v244, s[98:99] offset:16
	s_add_u32 s98, s98, 0x400000
	s_addc_u32 s99, s99, 0
	global_load_dwordx4 v[228:231], v244, s[98:99]
	global_load_dwordx4 v[232:235], v244, s[98:99] offset:16
	s_add_u32 s98, s98, 0x400000
	s_addc_u32 s99, s99, 0
	s_waitcnt vmcnt(14)
	v_cvt_pk_bf16_f32 v236, v154, v155
	v_cvt_pk_bf16_f32 v237, v156, v157
	v_cvt_pk_bf16_f32 v238, v158, v159
	v_cvt_pk_bf16_f32 v239, v160, v161
	global_store_dwordx4 v245, v[236:239], s[100:101]
	s_add_u32 s100, s100, 0x200000
	s_addc_u32 s101, s101, 0
	global_load_dwordx4 v[154:157], v244, s[98:99]
	global_load_dwordx4 v[158:161], v244, s[98:99] offset:16
	s_add_u32 s98, s98, 0x400000
	s_addc_u32 s99, s99, 0
	s_waitcnt vmcnt(15)
	v_cvt_pk_bf16_f32 v240, v162, v163
	v_cvt_pk_bf16_f32 v241, v164, v165
	v_cvt_pk_bf16_f32 v242, v166, v167
	v_cvt_pk_bf16_f32 v243, v168, v169
	global_store_dwordx4 v245, v[240:243], s[100:101]
	s_add_u32 s100, s100, 0x200000
	s_addc_u32 s101, s101, 0
	global_load_dwordx4 v[162:165], v244, s[98:99]
	global_load_dwordx4 v[166:169], v244, s[98:99] offset:16
	s_add_u32 s98, s98, 0x400000
	s_addc_u32 s99, s99, 0
	s_waitcnt vmcnt(16)
	v_cvt_pk_bf16_f32 v236, v170, v171
	v_cvt_pk_bf16_f32 v237, v172, v173
	v_cvt_pk_bf16_f32 v238, v174, v175
	v_cvt_pk_bf16_f32 v239, v176, v177
	global_store_dwordx4 v245, v[236:239], s[100:101]
	s_add_u32 s100, s100, 0x200000
	s_addc_u32 s101, s101, 0
	global_load_dwordx4 v[170:173], v244, s[98:99]
	global_load_dwordx4 v[174:177], v244, s[98:99] offset:16
	s_add_u32 s98, s98, 0x400000
	s_addc_u32 s99, s99, 0
	s_waitcnt vmcnt(17)
	v_cvt_pk_bf16_f32 v240, v178, v179
	v_cvt_pk_bf16_f32 v241, v180, v181
	v_cvt_pk_bf16_f32 v242, v182, v183
	v_cvt_pk_bf16_f32 v243, v184, v185
	global_store_dwordx4 v245, v[240:243], s[100:101]
	s_add_u32 s100, s100, 0x200000
	s_addc_u32 s101, s101, 0
	global_load_dwordx4 v[178:181], v244, s[98:99]
	global_load_dwordx4 v[182:185], v244, s[98:99] offset:16
	s_add_u32 s98, s98, 0x400000
	s_addc_u32 s99, s99, 0
	s_waitcnt vmcnt(18)
	v_cvt_pk_bf16_f32 v236, v186, v187
	v_cvt_pk_bf16_f32 v237, v188, v189
	v_cvt_pk_bf16_f32 v238, v190, v191
	v_cvt_pk_bf16_f32 v239, v192, v193
	global_store_dwordx4 v245, v[236:239], s[100:101]
	s_add_u32 s100, s100, 0x200000
	s_addc_u32 s101, s101, 0
	global_load_dwordx4 v[186:189], v244, s[98:99]
	global_load_dwordx4 v[190:193], v244, s[98:99] offset:16
	s_add_u32 s98, s98, 0x400000
	s_addc_u32 s99, s99, 0
	s_waitcnt vmcnt(19)
	v_cvt_pk_bf16_f32 v240, v194, v195
	v_cvt_pk_bf16_f32 v241, v196, v197
	v_cvt_pk_bf16_f32 v242, v198, v199
	v_cvt_pk_bf16_f32 v243, v200, v201
	global_store_dwordx4 v245, v[240:243], s[100:101]
	s_add_u32 s100, s100, 0x200000
	s_addc_u32 s101, s101, 0
	global_load_dwordx4 v[194:197], v244, s[98:99]
	global_load_dwordx4 v[198:201], v244, s[98:99] offset:16
	s_add_u32 s98, s98, 0x400000
	s_addc_u32 s99, s99, 0
	s_waitcnt vmcnt(20)
	v_cvt_pk_bf16_f32 v236, v208, v209
	v_cvt_pk_bf16_f32 v237, v210, v211
	v_cvt_pk_bf16_f32 v238, v212, v213
	v_cvt_pk_bf16_f32 v239, v214, v215
	global_store_dwordx4 v245, v[236:239], s[100:101]
	s_add_u32 s100, s100, 0x200000
	s_addc_u32 s101, s101, 0
	global_load_dwordx4 v[208:211], v244, s[98:99]
	global_load_dwordx4 v[212:215], v244, s[98:99] offset:16
	s_add_u32 s98, s98, 0x400000
	s_addc_u32 s99, s99, 0
	s_waitcnt vmcnt(21)
	v_cvt_pk_bf16_f32 v240, v228, v229
	v_cvt_pk_bf16_f32 v241, v230, v231
	v_cvt_pk_bf16_f32 v242, v232, v233
	v_cvt_pk_bf16_f32 v243, v234, v235
	global_store_dwordx4 v245, v[240:243], s[100:101]
	s_add_u32 s100, s100, 0x200000
	s_addc_u32 s101, s101, 0
	global_load_dwordx4 v[228:231], v244, s[98:99]
	global_load_dwordx4 v[232:235], v244, s[98:99] offset:16
	s_add_u32 s98, s98, 0x400000
	s_addc_u32 s99, s99, 0
	s_waitcnt vmcnt(21)
	v_cvt_pk_bf16_f32 v236, v154, v155
	v_cvt_pk_bf16_f32 v237, v156, v157
	v_cvt_pk_bf16_f32 v238, v158, v159
	v_cvt_pk_bf16_f32 v239, v160, v161
	global_store_dwordx4 v245, v[236:239], s[100:101]
	s_add_u32 s100, s100, 0x200000
	s_addc_u32 s101, s101, 0
	global_load_dwordx4 v[154:157], v244, s[98:99]
	global_load_dwordx4 v[158:161], v244, s[98:99] offset:16
	s_add_u32 s98, s98, 0x400000
	s_addc_u32 s99, s99, 0
	s_waitcnt vmcnt(21)
	v_cvt_pk_bf16_f32 v240, v162, v163
	v_cvt_pk_bf16_f32 v241, v164, v165
	v_cvt_pk_bf16_f32 v242, v166, v167
	v_cvt_pk_bf16_f32 v243, v168, v169
	global_store_dwordx4 v245, v[240:243], s[100:101]
	s_add_u32 s100, s100, 0x200000
	s_addc_u32 s101, s101, 0
	global_load_dwordx4 v[162:165], v244, s[98:99]
	global_load_dwordx4 v[166:169], v244, s[98:99] offset:16
	s_add_u32 s98, s98, 0x400000
	s_addc_u32 s99, s99, 0
	s_waitcnt vmcnt(21)
	v_cvt_pk_bf16_f32 v236, v170, v171
	v_cvt_pk_bf16_f32 v237, v172, v173
	v_cvt_pk_bf16_f32 v238, v174, v175
	v_cvt_pk_bf16_f32 v239, v176, v177
	global_store_dwordx4 v245, v[236:239], s[100:101]
	s_add_u32 s100, s100, 0x200000
	s_addc_u32 s101, s101, 0
	global_load_dwordx4 v[170:173], v244, s[98:99]
	global_load_dwordx4 v[174:177], v244, s[98:99] offset:16
	s_add_u32 s98, s98, 0x400000
	s_addc_u32 s99, s99, 0
	s_waitcnt vmcnt(21)
	v_cvt_pk_bf16_f32 v240, v178, v179
	v_cvt_pk_bf16_f32 v241, v180, v181
	v_cvt_pk_bf16_f32 v242, v182, v183
	v_cvt_pk_bf16_f32 v243, v184, v185
	global_store_dwordx4 v245, v[240:243], s[100:101]
	s_add_u32 s100, s100, 0x200000
	s_addc_u32 s101, s101, 0
	global_load_dwordx4 v[178:181], v244, s[98:99]
	global_load_dwordx4 v[182:185], v244, s[98:99] offset:16
	s_add_u32 s98, s98, 0x400000
	s_addc_u32 s99, s99, 0
	s_waitcnt vmcnt(21)
	v_cvt_pk_bf16_f32 v236, v186, v187
	v_cvt_pk_bf16_f32 v237, v188, v189
	v_cvt_pk_bf16_f32 v238, v190, v191
	v_cvt_pk_bf16_f32 v239, v192, v193
	global_store_dwordx4 v245, v[236:239], s[100:101]
	s_add_u32 s100, s100, 0x200000
	s_addc_u32 s101, s101, 0
	global_load_dwordx4 v[186:189], v244, s[98:99]
	global_load_dwordx4 v[190:193], v244, s[98:99] offset:16
	s_add_u32 s98, s98, 0x400000
	s_addc_u32 s99, s99, 0
	s_waitcnt vmcnt(21)
	v_cvt_pk_bf16_f32 v240, v194, v195
	v_cvt_pk_bf16_f32 v241, v196, v197
	v_cvt_pk_bf16_f32 v242, v198, v199
	v_cvt_pk_bf16_f32 v243, v200, v201
	global_store_dwordx4 v245, v[240:243], s[100:101]
	s_add_u32 s100, s100, 0x200000
	s_addc_u32 s101, s101, 0
	global_load_dwordx4 v[194:197], v244, s[98:99]
	global_load_dwordx4 v[198:201], v244, s[98:99] offset:16
	s_add_u32 s98, s98, 0x400000
	s_addc_u32 s99, s99, 0
	s_waitcnt vmcnt(21)
	v_cvt_pk_bf16_f32 v236, v208, v209
	v_cvt_pk_bf16_f32 v237, v210, v211
	v_cvt_pk_bf16_f32 v238, v212, v213
	v_cvt_pk_bf16_f32 v239, v214, v215
	global_store_dwordx4 v245, v[236:239], s[100:101]
	s_add_u32 s100, s100, 0x200000
	s_addc_u32 s101, s101, 0
	global_load_dwordx4 v[208:211], v244, s[98:99]
	global_load_dwordx4 v[212:215], v244, s[98:99] offset:16
	s_add_u32 s98, s98, 0x400000
	s_addc_u32 s99, s99, 0
	s_waitcnt vmcnt(21)
	v_cvt_pk_bf16_f32 v240, v228, v229
	v_cvt_pk_bf16_f32 v241, v230, v231
	v_cvt_pk_bf16_f32 v242, v232, v233
	v_cvt_pk_bf16_f32 v243, v234, v235
	global_store_dwordx4 v245, v[240:243], s[100:101]
	s_add_u32 s100, s100, 0x200000
	s_addc_u32 s101, s101, 0
	global_load_dwordx4 v[228:231], v244, s[98:99]
	global_load_dwordx4 v[232:235], v244, s[98:99] offset:16
	s_add_u32 s98, s98, 0x400000
	s_addc_u32 s99, s99, 0
	s_waitcnt vmcnt(21)
	v_cvt_pk_bf16_f32 v236, v154, v155
	v_cvt_pk_bf16_f32 v237, v156, v157
	v_cvt_pk_bf16_f32 v238, v158, v159
	v_cvt_pk_bf16_f32 v239, v160, v161
	global_store_dwordx4 v245, v[236:239], s[100:101]
	s_add_u32 s100, s100, 0x200000
	s_addc_u32 s101, s101, 0
	global_load_dwordx4 v[154:157], v244, s[98:99]
	global_load_dwordx4 v[158:161], v244, s[98:99] offset:16
	s_add_u32 s98, s98, 0x400000
	s_addc_u32 s99, s99, 0
	s_waitcnt vmcnt(21)
	v_cvt_pk_bf16_f32 v240, v162, v163
	v_cvt_pk_bf16_f32 v241, v164, v165
	v_cvt_pk_bf16_f32 v242, v166, v167
	v_cvt_pk_bf16_f32 v243, v168, v169
	global_store_dwordx4 v245, v[240:243], s[100:101]
	s_add_u32 s100, s100, 0x200000
	s_addc_u32 s101, s101, 0
	global_load_dwordx4 v[162:165], v244, s[98:99]
	global_load_dwordx4 v[166:169], v244, s[98:99] offset:16
	s_add_u32 s98, s98, 0x400000
	s_addc_u32 s99, s99, 0
	s_waitcnt vmcnt(21)
	v_cvt_pk_bf16_f32 v236, v170, v171
	v_cvt_pk_bf16_f32 v237, v172, v173
	v_cvt_pk_bf16_f32 v238, v174, v175
	v_cvt_pk_bf16_f32 v239, v176, v177
	global_store_dwordx4 v245, v[236:239], s[100:101]
	s_add_u32 s100, s100, 0x200000
	s_addc_u32 s101, s101, 0
	global_load_dwordx4 v[170:173], v244, s[98:99]
	global_load_dwordx4 v[174:177], v244, s[98:99] offset:16
	s_add_u32 s98, s98, 0x400000
	s_addc_u32 s99, s99, 0
	s_waitcnt vmcnt(21)
	v_cvt_pk_bf16_f32 v240, v178, v179
	v_cvt_pk_bf16_f32 v241, v180, v181
	v_cvt_pk_bf16_f32 v242, v182, v183
	v_cvt_pk_bf16_f32 v243, v184, v185
	global_store_dwordx4 v245, v[240:243], s[100:101]
	s_add_u32 s100, s100, 0x200000
	s_addc_u32 s101, s101, 0
	global_load_dwordx4 v[178:181], v244, s[98:99]
	global_load_dwordx4 v[182:185], v244, s[98:99] offset:16
	s_add_u32 s98, s98, 0x400000
	s_addc_u32 s99, s99, 0
	s_waitcnt vmcnt(21)
	v_cvt_pk_bf16_f32 v236, v186, v187
	v_cvt_pk_bf16_f32 v237, v188, v189
	v_cvt_pk_bf16_f32 v238, v190, v191
	v_cvt_pk_bf16_f32 v239, v192, v193
	global_store_dwordx4 v245, v[236:239], s[100:101]
	s_add_u32 s100, s100, 0x200000
	s_addc_u32 s101, s101, 0
	global_load_dwordx4 v[186:189], v244, s[98:99]
	global_load_dwordx4 v[190:193], v244, s[98:99] offset:16
	s_add_u32 s98, s98, 0x400000
	s_addc_u32 s99, s99, 0
	s_waitcnt vmcnt(21)
	v_cvt_pk_bf16_f32 v240, v194, v195
	v_cvt_pk_bf16_f32 v241, v196, v197
	v_cvt_pk_bf16_f32 v242, v198, v199
	v_cvt_pk_bf16_f32 v243, v200, v201
	global_store_dwordx4 v245, v[240:243], s[100:101]
	s_add_u32 s100, s100, 0x200000
	s_addc_u32 s101, s101, 0
	global_load_dwordx4 v[194:197], v244, s[98:99]
	global_load_dwordx4 v[198:201], v244, s[98:99] offset:16
	s_add_u32 s98, s98, 0x400000
	s_addc_u32 s99, s99, 0
	s_waitcnt vmcnt(21)
	v_cvt_pk_bf16_f32 v236, v208, v209
	v_cvt_pk_bf16_f32 v237, v210, v211
	v_cvt_pk_bf16_f32 v238, v212, v213
	v_cvt_pk_bf16_f32 v239, v214, v215
	global_store_dwordx4 v245, v[236:239], s[100:101]
	s_add_u32 s100, s100, 0x200000
	s_addc_u32 s101, s101, 0
	global_load_dwordx4 v[208:211], v244, s[98:99]
	global_load_dwordx4 v[212:215], v244, s[98:99] offset:16
	s_add_u32 s98, s98, 0x400000
	s_addc_u32 s99, s99, 0
	s_waitcnt vmcnt(21)
	v_cvt_pk_bf16_f32 v240, v228, v229
	v_cvt_pk_bf16_f32 v241, v230, v231
	v_cvt_pk_bf16_f32 v242, v232, v233
	v_cvt_pk_bf16_f32 v243, v234, v235
	global_store_dwordx4 v245, v[240:243], s[100:101]
	s_add_u32 s100, s100, 0x200000
	s_addc_u32 s101, s101, 0
	global_load_dwordx4 v[228:231], v244, s[98:99]
	global_load_dwordx4 v[232:235], v244, s[98:99] offset:16
	s_add_u32 s98, s98, 0x400000
	s_addc_u32 s99, s99, 0
	s_waitcnt vmcnt(21)
	v_cvt_pk_bf16_f32 v236, v154, v155
	v_cvt_pk_bf16_f32 v237, v156, v157
	v_cvt_pk_bf16_f32 v238, v158, v159
	v_cvt_pk_bf16_f32 v239, v160, v161
	global_store_dwordx4 v245, v[236:239], s[100:101]
	s_add_u32 s100, s100, 0x200000
	s_addc_u32 s101, s101, 0
	s_waitcnt vmcnt(19)
	v_cvt_pk_bf16_f32 v240, v162, v163
	v_cvt_pk_bf16_f32 v241, v164, v165
	v_cvt_pk_bf16_f32 v242, v166, v167
	v_cvt_pk_bf16_f32 v243, v168, v169
	global_store_dwordx4 v245, v[240:243], s[100:101]
	s_add_u32 s100, s100, 0x200000
	s_addc_u32 s101, s101, 0
	s_waitcnt vmcnt(17)
	v_cvt_pk_bf16_f32 v236, v170, v171
	v_cvt_pk_bf16_f32 v237, v172, v173
	v_cvt_pk_bf16_f32 v238, v174, v175
	v_cvt_pk_bf16_f32 v239, v176, v177
	global_store_dwordx4 v245, v[236:239], s[100:101]
	s_add_u32 s100, s100, 0x200000
	s_addc_u32 s101, s101, 0
	s_waitcnt vmcnt(15)
	v_cvt_pk_bf16_f32 v240, v178, v179
	v_cvt_pk_bf16_f32 v241, v180, v181
	v_cvt_pk_bf16_f32 v242, v182, v183
	v_cvt_pk_bf16_f32 v243, v184, v185
	global_store_dwordx4 v245, v[240:243], s[100:101]
	s_add_u32 s100, s100, 0x200000
	s_addc_u32 s101, s101, 0
	s_waitcnt vmcnt(13)
	v_cvt_pk_bf16_f32 v236, v186, v187
	v_cvt_pk_bf16_f32 v237, v188, v189
	v_cvt_pk_bf16_f32 v238, v190, v191
	v_cvt_pk_bf16_f32 v239, v192, v193
	global_store_dwordx4 v245, v[236:239], s[100:101]
	s_add_u32 s100, s100, 0x200000
	s_addc_u32 s101, s101, 0
	s_waitcnt vmcnt(11)
	v_cvt_pk_bf16_f32 v240, v194, v195
	v_cvt_pk_bf16_f32 v241, v196, v197
	v_cvt_pk_bf16_f32 v242, v198, v199
	v_cvt_pk_bf16_f32 v243, v200, v201
	global_store_dwordx4 v245, v[240:243], s[100:101]
	s_add_u32 s100, s100, 0x200000
	s_addc_u32 s101, s101, 0
	s_waitcnt vmcnt(9)
	v_cvt_pk_bf16_f32 v236, v208, v209
	v_cvt_pk_bf16_f32 v237, v210, v211
	v_cvt_pk_bf16_f32 v238, v212, v213
	v_cvt_pk_bf16_f32 v239, v214, v215
	global_store_dwordx4 v245, v[236:239], s[100:101]
	s_add_u32 s100, s100, 0x200000
	s_addc_u32 s101, s101, 0
	s_waitcnt vmcnt(7)
	v_cvt_pk_bf16_f32 v240, v228, v229
	v_cvt_pk_bf16_f32 v241, v230, v231
	v_cvt_pk_bf16_f32 v242, v232, v233
	v_cvt_pk_bf16_f32 v243, v234, v235
	global_store_dwordx4 v245, v[240:243], s[100:101]
	s_add_u32 s100, s100, 0x200000
	s_addc_u32 s101, s101, 0
	s_branch .LBB0_33
	s_branch .LBB0_28
